# bias-table copy in PA/SA item prologues: two 16B loads per thread in one round trip instead of hipcc's serialized dword-pair ladder
# speedup vs baseline: 1.0089x; 1.0089x over previous
.LBB0_457:
	s_sext_i32_i16 s0, s2
	s_mulk_i32 s0, 0x2aab
	s_lshr_b32 s1, s0, 31
	s_ashr_i32 s20, s0, 17
	s_load_dwordx4 s[12:15], s[52:53], 0x80
	s_add_i32 s20, s20, s1
	s_mul_i32 s0, s20, 12
	s_sub_i32 s0, s2, s0
	s_sext_i32_i16 s16, s0
	v_mov_b32_e32 v100, v0
	s_mov_b64 s[0:1], 0
	s_waitcnt lgkmcnt(0)
	s_add_u32 s6, s12, s0
	s_movk_i32 s2, 0xa80
	s_addc_u32 s7, s13, s1
	s_mul_i32 s2, s16, 0x2a00
	s_add_u32 s2, s6, s2
	s_addc_u32 s3, s7, 0
	s_add_u32 s2, s2, 0x2900000
	s_addc_u32 s3, s3, 0
	v_lshlrev_b32_e32 v226, 4, v100
	v_add_u32_e32 v227, 0x2000, v226
	global_load_dwordx4 v[218:221], v226, s[2:3]
	v_cmp_gt_u32_e32 vcc, 0xa0, v100
	s_and_saveexec_b64 s[12:13], vcc
	global_load_dwordx4 v[222:225], v227, s[2:3]
	s_or_b64 exec, exec, s[12:13]
	s_load_dwordx16 s[56:71], s[52:53], 0x40
	s_and_b32 s12, 0xffff, s20
	s_lshl_b64 s[0:1], s[0:1], 2
	s_mul_i32 s2, s12, 0xc000
	v_and_b32_e32 v3, 15, v100
	s_waitcnt lgkmcnt(0)
	s_add_u32 s14, s70, s0
	s_addc_u32 s15, s71, s1
	s_add_u32 s68, s6, 0x4c00000
	s_addc_u32 s69, s7, 0
	s_lshl_b32 s0, s16, 7
	s_ashr_i32 s1, s0, 31
	s_add_u32 s2, s68, s2
	s_addc_u32 s3, s69, 0
	s_lshl_b64 s[66:67], s[0:1], 1
	s_add_u32 s2, s2, s66
	v_lshlrev_b32_e32 v4, 3, v3
	v_mov_b32_e32 v5, v2
	s_addc_u32 s3, s3, s67
	v_lshl_add_u64 v[4:5], s[2:3], 0, v[4:5]
	s_mov_b64 s[2:3], 0x6000000
	v_lshl_add_u64 v[6:7], v[4:5], 0, s[2:3]
	s_mov_b32 s2, 0x6000000
	v_add_co_u32_e32 v8, vcc, s2, v4
	s_mov_b64 s[2:3], 0x6003000
	s_nop 0
	v_addc_co_u32_e32 v9, vcc, 0, v5, vcc
	v_lshl_add_u64 v[10:11], v[4:5], 0, s[2:3]
	s_mov_b32 s2, 0x6003000
	v_add_co_u32_e32 v12, vcc, s2, v4
	s_mov_b64 s[2:3], 0x6006000
	s_nop 0
	v_addc_co_u32_e32 v13, vcc, 0, v5, vcc
	v_lshl_add_u64 v[14:15], v[4:5], 0, s[2:3]
	s_mov_b32 s2, 0x6006000
	v_add_co_u32_e32 v16, vcc, s2, v4
	s_mov_b64 s[2:3], 0x6009000
	s_nop 0
	v_addc_co_u32_e32 v17, vcc, 0, v5, vcc
	v_lshl_add_u64 v[18:19], v[4:5], 0, s[2:3]
	s_mov_b32 s2, 0x6009000
	v_add_co_u32_e32 v4, vcc, s2, v4
	global_load_dwordx2 v[8:9], v[8:9], off
	s_nop 0
	v_addc_co_u32_e32 v5, vcc, 0, v5, vcc
	global_load_dwordx2 v[10:11], v[10:11], off offset:128
	s_nop 0
	global_load_dwordx2 v[12:13], v[12:13], off
	s_nop 0
	global_load_dwordx2 v[6:7], v[6:7], off offset:128
	s_mul_i32 s20, s12, 0x600000
	global_load_dwordx2 v[16:17], v[16:17], off
	s_nop 0
	global_load_dwordx2 v[18:19], v[18:19], off offset:128
	s_nop 0
	global_load_dwordx2 v[4:5], v[4:5], off
	s_nop 0
	global_load_dwordx2 v[14:15], v[14:15], off offset:128
	v_lshlrev_b32_e32 v150, 2, v3
	s_mov_b32 s54, s12
	s_add_i32 s3, s0, s20
	s_lshl_b64 s[12:13], s[20:21], 2
	v_or_b32_e32 v22, s3, v150
	s_add_u32 s3, s14, s12
	s_addc_u32 s12, s15, s13
	s_lshl_b64 s[0:1], s[0:1], 2
	s_add_u32 s0, s3, s0
	v_mov_b32_e32 v21, v2
	v_lshlrev_b32_e32 v20, 4, v3
	s_addc_u32 s1, s12, s1
	v_ashrrev_i32_e32 v101, 4, v100
	v_and_b32_e32 v159, 3, v101
	v_lshlrev_b32_e32 v137, 2, v101
	s_mov_b32 s2, 0
	v_lshlrev_b32_e32 v136, 2, v22
	v_or_b32_e32 v160, 0x80, v159
	v_or_b32_e32 v161, 0x100, v159
	v_or_b32_e32 v162, 0x180, v159
	v_mov_b32_e32 v167, 0xe0ad78ec
	v_mov_b32_e32 v163, v137
	v_mov_b32_e32 v166, 0xe0ad78ec
	v_mov_b32_e32 v165, 0xe0ad78ec
	v_mov_b32_e32 v164, 0xe0ad78ec
	s_waitcnt vmcnt(8)
	v_add_u32_e32 v226, s51, v226
	ds_write_b128 v226, v[218:221]
	v_cmp_gt_u32_e32 vcc, 0xa0, v100
	s_and_saveexec_b64 vcc, vcc
	ds_write_b128 v226, v[222:225] offset:8192
	s_mov_b64 exec, vcc
	s_waitcnt lgkmcnt(0)
	s_barrier
	s_waitcnt vmcnt(7)
	v_lshlrev_b32_e32 v157, 16, v8
	v_and_b32_e32 v158, 0xffff0000, v8
	v_and_b32_e32 v135, 0xffff0000, v9
	v_lshlrev_b32_e32 v134, 16, v9
	s_waitcnt vmcnt(4)
	v_and_b32_e32 v133, 0xffff0000, v6
	s_waitcnt vmcnt(1)
	v_lshlrev_b32_e32 v151, 16, v4
	v_and_b32_e32 v152, 0xffff0000, v4
	v_and_b32_e32 v111, 0xffff0000, v5
	v_lshlrev_b32_e32 v110, 16, v5
	v_lshl_add_u64 v[4:5], s[0:1], 0, v[20:21]
	s_mov_b64 s[0:1], 0xa31c000
	v_lshl_add_u64 v[138:139], v[4:5], 0, s[0:1]
	v_mov_b32_e32 v4, 0
	v_lshlrev_b32_e32 v132, 16, v6
	v_and_b32_e32 v131, 0xffff0000, v7
	v_lshlrev_b32_e32 v130, 16, v7
	v_lshlrev_b32_e32 v155, 16, v12
	v_and_b32_e32 v156, 0xffff0000, v12
	v_and_b32_e32 v127, 0xffff0000, v13
	v_lshlrev_b32_e32 v126, 16, v13
	v_and_b32_e32 v125, 0xffff0000, v10
	v_lshlrev_b32_e32 v124, 16, v10
	v_and_b32_e32 v123, 0xffff0000, v11
	v_lshlrev_b32_e32 v122, 16, v11
	v_lshlrev_b32_e32 v153, 16, v16
	v_and_b32_e32 v154, 0xffff0000, v16
	v_and_b32_e32 v121, 0xffff0000, v17
	v_lshlrev_b32_e32 v120, 16, v17
	s_waitcnt vmcnt(0)
	v_and_b32_e32 v119, 0xffff0000, v14
	v_lshlrev_b32_e32 v118, 16, v14
	v_and_b32_e32 v117, 0xffff0000, v15
	v_lshlrev_b32_e32 v116, 16, v15
	v_and_b32_e32 v109, 0xffff0000, v18
	v_lshlrev_b32_e32 v108, 16, v18
	v_and_b32_e32 v107, 0xffff0000, v19
	v_lshlrev_b32_e32 v106, 16, v19
	v_mov_b32_e32 v5, v4
	v_mov_b32_e32 v6, v4
	v_mov_b32_e32 v7, v4
	v_mov_b32_e32 v8, v4
	v_mov_b32_e32 v9, v4
	v_mov_b32_e32 v10, v4
	v_mov_b32_e32 v11, v4
	v_mov_b32_e32 v16, v4
	v_mov_b32_e32 v17, v4
	v_mov_b32_e32 v18, v4
	v_mov_b32_e32 v19, v4
	v_mov_b32_e32 v12, v4
	v_mov_b32_e32 v13, v4
	v_mov_b32_e32 v14, v4
	v_mov_b32_e32 v15, v4
	v_mov_b32_e32 v24, v4
	v_mov_b32_e32 v25, v4
	v_mov_b32_e32 v26, v4
	v_mov_b32_e32 v27, v4
	v_mov_b32_e32 v20, v4
	v_mov_b32_e32 v21, v4
	v_mov_b32_e32 v22, v4
	v_mov_b32_e32 v23, v4
	v_mov_b32_e32 v32, v4
	v_mov_b32_e32 v33, v4
	v_mov_b32_e32 v34, v4
	v_mov_b32_e32 v35, v4
	v_mov_b32_e32 v28, v4
	v_mov_b32_e32 v29, v4
	v_mov_b32_e32 v30, v4
	v_mov_b32_e32 v31, v4
	v_mov_b32_e32 v104, v4
	v_mov_b32_e32 v105, v4
	v_mov_b32_e32 v102, v4
	v_mov_b32_e32 v103, v4

.LBB0_483:
	s_and_b64 vcc, exec, s[0:1]
	s_cbranch_vccz .LBB0_598
	s_and_b32 s0, s5, 0xffff
	s_mul_i32 s0, s0, 0xaaab
	s_lshr_b32 s39, s0, 21
	s_mul_i32 s0, s39, 48
	s_sub_i32 s0, s5, s0
	s_and_b32 s1, s0, 0xff
	s_mulk_i32 s1, 0xab
	s_load_dwordx4 s[12:15], s[52:53], 0x80
	s_bfe_u32 s2, s1, 0x5000b
	s_mul_i32 s3, s2, 12
	v_mov_b32_e32 v4, v0
	s_sub_i32 s0, s0, s3
	s_sub_i32 s42, 7, s39
	v_readfirstlane_b32 s40, v4
	s_and_b32 s44, s0, 0xff
	s_ashr_i32 s66, s40, 6
	s_mov_b64 s[6:7], 0
	s_waitcnt lgkmcnt(0)
	s_add_u32 s36, s12, s6
	s_addc_u32 s37, s13, s7
	s_add_u32 s68, s36, 0x4c00000
	v_and_b32_e32 v212, 31, v4
	s_addc_u32 s69, s37, 0
	s_lshl_b32 s41, s42, 8
	s_and_b32 s0, s1, 0xf800
	s_or_b32 s5, s0, s41
	v_lshlrev_b32_e32 v3, 3, v212
	v_or_b32_e32 v5, s5, v3
	v_add_u32_e32 v5, s66, v5
	v_mov_b64_e32 v[6:7], s[68:69]
	v_mad_i64_i32 v[6:7], s[0:1], v5, s19, v[6:7]
	v_bfe_u32 v211, v4, 5, 1
	s_lshl_b32 s0, s44, 8
	s_mov_b32 s1, s21
	v_lshl_add_u64 v[6:7], v[6:7], 0, s[0:1]
	v_lshlrev_b32_e32 v198, 4, v211
	v_mov_b32_e32 v199, v2
	v_lshl_add_u64 v[6:7], v[6:7], 0, v[198:199]
	s_lshl_b32 s43, s66, 2
	v_bfe_u32 v197, v4, 4, 2
	global_load_dwordx4 v[162:165], v[6:7], off
	global_load_dwordx4 v[166:169], v[6:7], off offset:32
	global_load_dwordx4 v[170:173], v[6:7], off offset:64
	global_load_dwordx4 v[174:177], v[6:7], off offset:96
	global_load_dwordx4 v[178:181], v[6:7], off offset:128
	global_load_dwordx4 v[182:185], v[6:7], off offset:160
	global_load_dwordx4 v[186:189], v[6:7], off offset:192
	global_load_dwordx4 v[190:193], v[6:7], off offset:224
	v_or_b32_e32 v5, s43, v197
	v_lshlrev_b32_e32 v6, 4, v4
	v_and_b32_e32 v6, 0xf0, v6
	v_lshlrev_b32_e32 v7, 4, v5
	s_movk_i32 s0, 0x70
	v_bitop3_b32 v6, v7, v6, s0 bitop3:0x6c
	s_ashr_i32 s1, s40, 4
	v_lshrrev_b32_e32 v8, 1, v6
	s_and_b32 s3, s1, 0x3ffffff0
	v_lshrrev_b32_e32 v6, 2, v4
	v_lshrrev_b32_e32 v199, 1, v4
	s_lshr_b32 s1, s1, 1
	s_lshl_b32 s0, s66, 1
	v_and_or_b32 v6, v6, 3, s3
	v_and_b32_e32 v7, 8, v199
	s_and_b32 s1, s1, 4
	s_lshl_b32 s20, s44, 7
	v_or3_b32 v6, v6, v7, s1
	v_and_or_b32 v7, s0, 2, v211
	v_lshlrev_b32_e32 v210, 3, v4
	v_lshlrev_b32_e32 v7, 5, v7
	v_and_b32_e32 v9, 24, v210
	s_add_i32 s0, s20, 0xc00
	s_ashr_i32 s67, s66, 31
	v_lshlrev_b32_e32 v10, 2, v6
	v_or3_b32 v6, v7, v9, s0
	v_mov_b32_e32 v7, v2
	s_movk_i32 s3, 0x1800
	s_mul_i32 s2, s2, 0x1800000
	v_mad_i64_i32 v[200:201], s[0:1], v10, s3, v[6:7]
	s_add_u32 s70, s68, s2
	v_lshlrev_b32_e32 v5, 2, v5
	s_addc_u32 s71, s69, 0
	s_lshl_b32 s0, s66, 10
	v_mov_b64_e32 v[6:7], s[20:21]
	s_add_i32 s38, s0, 0
	v_mad_i64_i32 v[202:203], s[0:1], v5, s3, v[6:7]
	v_or_b32_e32 v202, v202, v8
	v_lshl_add_u64 v[6:7], v[202:203], 1, s[70:71]
	s_mov_b64 s[0:1], 0xc00
	v_lshl_add_u64 v[8:9], v[6:7], 0, s[0:1]
	s_add_i32 s0, s38, 0x8000
	s_mov_b32 m0, s38
	v_lshl_add_u64 v[10:11], v[200:201], 1, s[70:71]
	global_load_lds_dwordx4 v[8:9], off
	s_mov_b32 m0, s0
	s_mov_b64 s[0:1], 0x3c00
	global_load_lds_dwordx4 v[10:11], off
	v_lshl_add_u64 v[8:9], v[6:7], 0, s[0:1]
	s_add_i32 m0, s38, 0x2000
	s_mov_b64 s[0:1], 0x3000
	global_load_lds_dwordx4 v[8:9], off
	v_lshl_add_u64 v[8:9], v[10:11], 0, s[0:1]
	s_add_i32 m0, s38, 0xa000
	s_mov_b64 s[0:1], 0x6c00
	global_load_lds_dwordx4 v[8:9], off
	v_lshl_add_u64 v[8:9], v[6:7], 0, s[0:1]
	s_add_i32 m0, s38, 0x4000
	s_mov_b64 s[0:1], 0x6000
	global_load_lds_dwordx4 v[8:9], off
	v_lshl_add_u64 v[8:9], v[10:11], 0, s[0:1]
	s_add_i32 m0, s38, 0xc000
	s_mov_b64 s[0:1], 0x9c00
	global_load_lds_dwordx4 v[8:9], off
	v_lshl_add_u64 v[6:7], v[6:7], 0, s[0:1]
	s_add_i32 m0, s38, 0x6000
	s_mov_b64 s[0:1], 0x9000
	global_load_lds_dwordx4 v[6:7], off
	v_lshl_add_u64 v[6:7], v[10:11], 0, s[0:1]
	s_add_i32 m0, s38, 0xe000
	s_movk_i32 s0, 0xa80
	global_load_lds_dwordx4 v[6:7], off
	s_mul_i32 s2, s44, 0x2a00
	s_add_u32 s2, s36, s2
	s_addc_u32 s3, s37, 0
	s_add_u32 s2, s2, 0x2900000
	s_addc_u32 s3, s3, 0
	v_lshlrev_b32_e32 v108, 4, v0
	v_add_u32_e32 v109, 0x2000, v108
	global_load_dwordx4 v[100:103], v108, s[2:3]
	v_cmp_gt_u32_e32 vcc, 0xa0, v0
	s_and_saveexec_b64 s[12:13], vcc
	global_load_dwordx4 v[104:107], v109, s[2:3]
	s_or_b64 exec, exec, s[12:13]
	v_and_b32_e32 v213, 63, v4
	v_lshlrev_b32_e32 v4, 3, v213
	v_lshlrev_b32_e32 v6, 4, v213
	s_and_b32 s0, s40, 0x3fffffc0
	v_and_b32_e32 v5, 24, v4
	v_and_b32_e32 v6, 0xc0, v6
	v_lshlrev_b32_e32 v8, 1, v213
	s_lshl_b32 s0, s0, 2
	v_or_b32_e32 v7, v5, v6
	v_and_b32_e32 v8, 32, v8
	v_and_b32_e32 v4, 0x100, v4
	s_add_i32 s2, s0, 0
	v_or3_b32 v214, v7, v8, v4
	v_lshlrev_b32_e32 v7, 4, v212
	s_movk_i32 s0, 0x70
	v_and_b32_e32 v9, 0x70, v7
	v_bitop3_b32 v216, v198, v7, s0 bitop3:0x78
	s_movk_i32 s0, 0x60
	v_bitop3_b32 v219, v198, v9, s0 bitop3:0x36
	s_movk_i32 s0, 0x80
	v_bitop3_b32 v220, v198, v9, s0 bitop3:0x36
	s_movk_i32 s0, 0xa0
	v_bitop3_b32 v221, v198, v9, s0 bitop3:0x36
	s_movk_i32 s0, 0xc0
	v_bitop3_b32 v223, v198, v9, s0 bitop3:0x36
	s_movk_i32 s0, 0xe0
	v_bitop3_b32 v224, v198, v9, s0 bitop3:0x36
	s_add_i32 s0, s41, s66
	s_addk_i32 s0, 0x180
	v_add_u32_e32 v225, s0, v3
	v_lshl_add_u32 v3, v212, 5, s43
	v_lshlrev_b32_e32 v16, 6, v211
	v_sub_u32_e32 v3, v3, v16
	s_lshl_b32 s0, s39, 10
	v_subrev_u32_e32 v226, s0, v3
	s_add_i32 s0, 0, 0x8000
	s_waitcnt vmcnt(0)
	v_add_u32_e32 v108, s51, v108
	ds_write_b128 v108, v[100:103]
	v_cmp_gt_u32_e32 vcc, 0xa0, v0
	s_and_saveexec_b64 vcc, vcc
	ds_write_b128 v108, v[104:107] offset:8192
	s_mov_b64 exec, vcc
	v_lshlrev_b32_e32 v215, 8, v212
	v_or_b32_e32 v7, 32, v198
	v_or_b32_e32 v10, 64, v198
	v_or_b32_e32 v11, 0x60, v198
	v_or_b32_e32 v12, 0x80, v198
	v_or_b32_e32 v13, 0xa0, v198
	v_or_b32_e32 v14, 0xc0, v198
	v_or_b32_e32 v15, 0xe0, v198
	v_add3_u32 v3, v4, s0, v6
	v_mov_b32_e32 v16, v2
	v_mov_b32_e32 v17, v2
	s_lshl_b32 s12, s42, 1
	s_add_i32 s2, s2, 0x22a00
	v_bitop3_b32 v217, v198, v9, 32 bitop3:0x36
	v_bitop3_b32 v218, v198, v9, 64 bitop3:0x36
	s_bfe_u32 s13, s40, 0x20006
	v_add3_u32 v227, v3, v8, v5
	v_bitop3_b32 v228, v198, v215, v9 bitop3:0xde
	v_bitop3_b32 v229, v7, v215, v9 bitop3:0xde
	v_bitop3_b32 v230, v10, v215, v9 bitop3:0xde
	v_bitop3_b32 v231, v11, v215, v9 bitop3:0xde
	v_bitop3_b32 v232, v12, v215, v9 bitop3:0xde
	v_bitop3_b32 v233, v13, v215, v9 bitop3:0xde
	v_bitop3_b32 v234, v15, v215, v9 bitop3:0xde
	v_bitop3_b32 v235, v14, v215, v9 bitop3:0xde
	v_mov_b32_e32 v3, v2
	v_mov_b32_e32 v4, v2
	v_mov_b32_e32 v5, v2
	v_mov_b32_e32 v6, v2
	v_mov_b32_e32 v7, v2
	v_mov_b32_e32 v8, v2
	v_mov_b32_e32 v9, v2
	v_mov_b32_e32 v10, v2
	v_mov_b32_e32 v11, v2
	v_mov_b32_e32 v12, v2
	v_mov_b32_e32 v13, v2
	v_mov_b32_e32 v14, v2
	v_mov_b32_e32 v15, v2
	v_mov_b64_e32 v[32:33], v[16:17]
	v_mov_b64_e32 v[48:49], v[16:17]
	v_mov_b64_e32 v[64:65], v[16:17]
	v_mov_b64_e32 v[80:81], v[16:17]
	s_add_i32 s3, s12, 2
	s_add_i32 s12, s12, -1
	v_cmp_gt_u32_e64 s[6:7], 32, v213
	v_lshl_add_u32 v222, v212, 2, s2
	s_lshl_b32 s14, s13, 13
	s_mov_b32 s15, 0
	v_mov_b32_e32 v237, 0xe0ad78ec
	v_mov_b32_e32 v236, 0
	v_mov_b64_e32 v[30:31], v[14:15]
	v_mov_b64_e32 v[28:29], v[12:13]
	v_mov_b64_e32 v[26:27], v[10:11]
	v_mov_b64_e32 v[24:25], v[8:9]
	v_mov_b64_e32 v[22:23], v[6:7]
	v_mov_b64_e32 v[20:21], v[4:5]
	v_mov_b64_e32 v[18:19], v[2:3]
	v_mov_b64_e32 v[46:47], v[14:15]
	v_mov_b64_e32 v[44:45], v[12:13]
	v_mov_b64_e32 v[42:43], v[10:11]
	v_mov_b64_e32 v[40:41], v[8:9]
	v_mov_b64_e32 v[38:39], v[6:7]
	v_mov_b64_e32 v[36:37], v[4:5]
	v_mov_b64_e32 v[34:35], v[2:3]
	v_mov_b64_e32 v[62:63], v[14:15]
	v_mov_b64_e32 v[60:61], v[12:13]
	v_mov_b64_e32 v[58:59], v[10:11]
	v_mov_b64_e32 v[56:57], v[8:9]
	v_mov_b64_e32 v[54:55], v[6:7]
	v_mov_b64_e32 v[52:53], v[4:5]
	v_mov_b64_e32 v[50:51], v[2:3]
	v_mov_b64_e32 v[78:79], v[14:15]
	v_mov_b64_e32 v[76:77], v[12:13]
	v_mov_b64_e32 v[74:75], v[10:11]
	v_mov_b64_e32 v[72:73], v[8:9]
	v_mov_b64_e32 v[70:71], v[6:7]
	v_mov_b64_e32 v[68:69], v[4:5]
	v_mov_b64_e32 v[66:67], v[2:3]
	s_mov_b32 s25, 0
	s_waitcnt vmcnt(0) lgkmcnt(0)
	s_barrier
	s_add_i32 s24, s25, 1
	s_cmp_ge_u32 s24, s3
	s_cbranch_scc0 .LBB0_499
	s_branch .LBB0_500
